# scan consumer: y partials of four steps reduced together by a transposing butterfly (11 vector ops and one LDS store per four steps instead of 16 and four)
# speedup vs baseline: 1.0333x; 1.0123x over previous
; __device__ __forceinline__ void rwkv_prompt_unit(const Params& p, int l, int b, int h, int ibase, float* sf) {
;     ...
;             const float* bf_ = sf + (c & 1) * 12288 + jg; float* sY = sYb + (c & 1) * 512; const float* vb_ = sf + (c & 1) * 12288 + 6144 + ibase + rl;
;             f32x4 R[2], W[2], K[2], A[2], B[2]; float V[2];
;     ...
;             RW_LOAD(R, W, K, A, B, V, 0);
;             float pyprev = 0.f;
; #pragma unroll
;             for (int g = 0; g < 16; ++g) {
;                 f32x4 Rn[2], Wn[2], Kn[2], An[2], Bn[2]; float Vn[2];
;                 if (g + 1 < 16) RW_LOAD(Rn, Wn, Kn, An, Bn, Vn, g + 1);
;                 __builtin_amdgcn_sched_barrier(0);
; #pragma unroll
;                 for (int u = 0; u < 2; ++u) {
;                     const f32x2v a01 = {A[u].x, A[u].y}, a23 = {A[u].z, A[u].w}, w01 = {W[u].x, W[u].y}, w23 = {W[u].z, W[u].w}, b01 = {B[u].x, B[u].y}, b23 = {B[u].z, B[u].w};
;                     const f32x2v k01 = {K[u].x, K[u].y}, k23 = {K[u].z, K[u].w}, r01 = {R[u].x, R[u].y}, r23 = {R[u].z, R[u].w};
;                     f32x2v pa = S01 * a01; pa = __builtin_elementwise_fma(S23, a23, pa);
;                     float ra = pa.x + pa.y, rb = pyprev;
;                     ra += dppf<0xB1, 0xF>(ra); rb += dppf<0xB1, 0xF>(rb);
;                     ra += dppf<0x4E, 0xF>(ra); rb += dppf<0x4E, 0xF>(rb);
;                     ra += dppf<0x124, 0xF>(ra); rb += dppf<0x124, 0xF>(rb);
;                     ra += dppf<0x128, 0xF>(ra); rb += dppf<0x128, 0xF>(rb);
;                     if ((g * 2 + u) > 0 && (lane & 15) == 0) sY[(g * 2 + u - 1) * 16 + rl] = rb;
;                     const f32x2v sa2 = {ra, ra}, v2 = {V[u], V[u]};
;                     S01 = __builtin_elementwise_fma(S01, w01, __builtin_elementwise_fma(sa2, b01, v2 * k01));
;                     S23 = __builtin_elementwise_fma(S23, w23, __builtin_elementwise_fma(sa2, b23, v2 * k23));
;                     f32x2v py = S01 * r01; py = __builtin_elementwise_fma(S23, r23, py);
;                     pyprev = py.x + py.y;
.LBB0_964:
	s_and_b64 vcc, exec, s[8:9]
	s_cbranch_vccz .LBB0_1029
	s_setprio 0
	s_and_b32 s8, s15, 1
	s_mul_i32 s9, s8, 0xc000
	v_lshl_add_u32 v212, v176, 2, s9
	s_add_i32 s9, s9, s11
	v_lshl_add_u32 v213, v210, 2, s9
	ds_read_b128 v[50:53], v212 offset:32768
	ds_read_b128 v[62:65], v212 offset:16384
	ds_read_b128 v[54:57], v212 offset:8192
	ds_read_b128 v[58:61], v212 offset:40960
	ds_read_b128 v[66:69], v212 offset:0
	ds_read2st64_b32 v[110:111], v213 offset0:96 offset1:97
	ds_read_b128 v[70:73], v212 offset:33024
	ds_read_b128 v[82:85], v212 offset:16640
	ds_read_b128 v[74:77], v212 offset:8448
	ds_read_b128 v[78:81], v212 offset:41216
	ds_read_b128 v[86:89], v212 offset:256
	s_lshl_b32 s8, s8, 11
	s_add_i32 s8, s8, 0x18000
	v_lshl_add_u32 v211, v210, 2, s8
	v_and_b32_e32 v137, 3, v207
	v_lshl_add_u32 v211, v137, 6, v211
	s_add_i32 s8, s8, 0x1000
	v_and_b32_e32 v137, 63, v207
	v_lshl_add_u32 v137, v137, 2, s8
	v_and_b32_e32 v186, 15, v207
	v_cmp_gt_u32_e32 vcc, 4, v186
	s_nop 1
	v_cndmask_b32_e32 v211, v137, v211, vcc
	v_and_b32_e32 v186, 1, v207
	v_cmp_ne_u32_e64 s[8:9], 0, v186
	v_and_b32_e32 v186, 2, v207
	v_cmp_ne_u32_e32 vcc, 0, v186
	s_waitcnt lgkmcnt(5)
	v_pk_mul_f32 v[114:115], v[46:47], v[50:51]
	s_nop 0
	v_pk_fma_f32 v[114:115], v[48:49], v[52:53], v[114:115]
	s_nop 0
	v_add_f32_e32 v116, v114, v115
	v_pk_mul_f32 v[120:121], v[62:63], v[110:111] op_sel_hi:[1,0]
	v_pk_mul_f32 v[122:123], v[64:65], v[110:111] op_sel_hi:[1,0]
	v_add_f32_dpp v116, v116, v116 quad_perm:[1,0,3,2] row_mask:0xf bank_mask:0xf bound_ctrl:1
	v_pk_fma_f32 v[124:125], v[46:47], v[54:55], v[120:121]
	v_pk_fma_f32 v[126:127], v[48:49], v[56:57], v[122:123]
	v_add_f32_dpp v116, v116, v116 quad_perm:[2,3,0,1] row_mask:0xf bank_mask:0xf bound_ctrl:1
	ds_read_b128 v[90:93], v212 offset:33280
	ds_read_b128 v[102:105], v212 offset:16896
	v_add_f32_dpp v116, v116, v116 row_ror:4 row_mask:0xf bank_mask:0xf bound_ctrl:1
	ds_read_b128 v[94:97], v212 offset:8704
	ds_read_b128 v[98:101], v212 offset:41472
	v_add_f32_dpp v116, v116, v116 row_ror:8 row_mask:0xf bank_mask:0xf bound_ctrl:1
	ds_read_b128 v[106:109], v212 offset:512
	v_pk_fma_f32 v[46:47], v[116:117], v[58:59], v[124:125] op_sel_hi:[0,1,1]
	v_pk_fma_f32 v[48:49], v[116:117], v[60:61], v[126:127] op_sel_hi:[0,1,1]
	ds_read2st64_b32 v[112:113], v213 offset0:98 offset1:99
	s_waitcnt lgkmcnt(6)
	v_pk_mul_f32 v[114:115], v[46:47], v[70:71]
	v_pk_mul_f32 v[118:119], v[46:47], v[66:67]
	v_pk_fma_f32 v[114:115], v[48:49], v[72:73], v[114:115]
	v_pk_fma_f32 v[118:119], v[48:49], v[68:69], v[118:119]
	v_add_f32_e32 v116, v114, v115
	v_add_f32_e32 v129, v118, v119
	v_pk_mul_f32 v[120:121], v[82:83], v[110:111] op_sel:[0,1] op_sel_hi:[1,1]
	v_pk_mul_f32 v[122:123], v[84:85], v[110:111] op_sel:[0,1] op_sel_hi:[1,1]
	v_add_f32_dpp v116, v116, v116 quad_perm:[1,0,3,2] row_mask:0xf bank_mask:0xf bound_ctrl:1
	v_pk_fma_f32 v[124:125], v[46:47], v[74:75], v[120:121]
	v_pk_fma_f32 v[126:127], v[48:49], v[76:77], v[122:123]
	v_add_f32_dpp v116, v116, v116 quad_perm:[2,3,0,1] row_mask:0xf bank_mask:0xf bound_ctrl:1
	ds_read_b128 v[50:53], v212 offset:33536
	ds_read_b128 v[62:65], v212 offset:17152
	v_add_f32_dpp v116, v116, v116 row_ror:4 row_mask:0xf bank_mask:0xf bound_ctrl:1
	ds_read_b128 v[54:57], v212 offset:8960
	ds_read_b128 v[58:61], v212 offset:41728
	v_add_f32_dpp v116, v116, v116 row_ror:8 row_mask:0xf bank_mask:0xf bound_ctrl:1
	ds_read_b128 v[66:69], v212 offset:768
	v_pk_fma_f32 v[46:47], v[116:117], v[78:79], v[124:125] op_sel_hi:[0,1,1]
	v_pk_fma_f32 v[48:49], v[116:117], v[80:81], v[126:127] op_sel_hi:[0,1,1]
	s_waitcnt lgkmcnt(5)
	v_pk_mul_f32 v[114:115], v[46:47], v[90:91]
	v_pk_mul_f32 v[118:119], v[46:47], v[86:87]
	v_pk_fma_f32 v[114:115], v[48:49], v[92:93], v[114:115]
	v_pk_fma_f32 v[118:119], v[48:49], v[88:89], v[118:119]
	v_add_f32_e32 v116, v114, v115
	v_add_f32_e32 v130, v118, v119
	v_pk_mul_f32 v[120:121], v[102:103], v[112:113] op_sel_hi:[1,0]
	v_pk_mul_f32 v[122:123], v[104:105], v[112:113] op_sel_hi:[1,0]
	v_add_f32_dpp v116, v116, v116 quad_perm:[1,0,3,2] row_mask:0xf bank_mask:0xf bound_ctrl:1
	v_pk_fma_f32 v[124:125], v[46:47], v[94:95], v[120:121]
	v_pk_fma_f32 v[126:127], v[48:49], v[96:97], v[122:123]
	v_add_f32_dpp v116, v116, v116 quad_perm:[2,3,0,1] row_mask:0xf bank_mask:0xf bound_ctrl:1
	ds_read_b128 v[70:73], v212 offset:33792
	ds_read_b128 v[82:85], v212 offset:17408
	v_add_f32_dpp v116, v116, v116 row_ror:4 row_mask:0xf bank_mask:0xf bound_ctrl:1
	ds_read_b128 v[74:77], v212 offset:9216
	ds_read_b128 v[78:81], v212 offset:41984
	v_add_f32_dpp v116, v116, v116 row_ror:8 row_mask:0xf bank_mask:0xf bound_ctrl:1
	ds_read_b128 v[86:89], v212 offset:1024
	v_pk_fma_f32 v[46:47], v[116:117], v[98:99], v[124:125] op_sel_hi:[0,1,1]
	v_pk_fma_f32 v[48:49], v[116:117], v[100:101], v[126:127] op_sel_hi:[0,1,1]
	ds_read2st64_b32 v[110:111], v213 offset0:100 offset1:101
	s_waitcnt lgkmcnt(6)
	v_pk_mul_f32 v[114:115], v[46:47], v[50:51]
	v_pk_mul_f32 v[118:119], v[46:47], v[106:107]
	v_pk_fma_f32 v[114:115], v[48:49], v[52:53], v[114:115]
	v_pk_fma_f32 v[118:119], v[48:49], v[108:109], v[118:119]
	v_add_f32_e32 v116, v114, v115
	v_add_f32_e32 v131, v118, v119
	v_pk_mul_f32 v[120:121], v[62:63], v[112:113] op_sel:[0,1] op_sel_hi:[1,1]
	v_pk_mul_f32 v[122:123], v[64:65], v[112:113] op_sel:[0,1] op_sel_hi:[1,1]
	v_add_f32_dpp v116, v116, v116 quad_perm:[1,0,3,2] row_mask:0xf bank_mask:0xf bound_ctrl:1
	v_pk_fma_f32 v[124:125], v[46:47], v[54:55], v[120:121]
	v_pk_fma_f32 v[126:127], v[48:49], v[56:57], v[122:123]
	v_add_f32_dpp v116, v116, v116 quad_perm:[2,3,0,1] row_mask:0xf bank_mask:0xf bound_ctrl:1
	ds_read_b128 v[90:93], v212 offset:34048
	ds_read_b128 v[102:105], v212 offset:17664
	v_add_f32_dpp v116, v116, v116 row_ror:4 row_mask:0xf bank_mask:0xf bound_ctrl:1
	ds_read_b128 v[94:97], v212 offset:9472
	ds_read_b128 v[98:101], v212 offset:42240
	v_add_f32_dpp v116, v116, v116 row_ror:8 row_mask:0xf bank_mask:0xf bound_ctrl:1
	ds_read_b128 v[106:109], v212 offset:1280
	v_pk_fma_f32 v[46:47], v[116:117], v[58:59], v[124:125] op_sel_hi:[0,1,1]
	v_pk_fma_f32 v[48:49], v[116:117], v[60:61], v[126:127] op_sel_hi:[0,1,1]
	s_waitcnt lgkmcnt(5)
; __device__ __forceinline__ void rwkv_prompt_unit(const Params& p, int l, int b, int h, int ibase, float* sf) {
;     ...
;             for (int g = 0; g < 16; ++g) {
;                 f32x4 Rn[2], Wn[2], Kn[2], An[2], Bn[2]; float Vn[2];
;                 if (g + 1 < 16) RW_LOAD(Rn, Wn, Kn, An, Bn, Vn, g + 1);
;                 __builtin_amdgcn_sched_barrier(0);
; #pragma unroll
;                 for (int u = 0; u < 2; ++u) {
;                     const f32x2v a01 = {A[u].x, A[u].y}, a23 = {A[u].z, A[u].w}, w01 = {W[u].x, W[u].y}, w23 = {W[u].z, W[u].w}, b01 = {B[u].x, B[u].y}, b23 = {B[u].z, B[u].w};
;                     const f32x2v k01 = {K[u].x, K[u].y}, k23 = {K[u].z, K[u].w}, r01 = {R[u].x, R[u].y}, r23 = {R[u].z, R[u].w};
;                     f32x2v pa = S01 * a01; pa = __builtin_elementwise_fma(S23, a23, pa);
;                     float ra = pa.x + pa.y, rb = pyprev;
;                     ra += dppf<0xB1, 0xF>(ra); rb += dppf<0xB1, 0xF>(rb);
;                     ra += dppf<0x4E, 0xF>(ra); rb += dppf<0x4E, 0xF>(rb);
;                     ra += dppf<0x124, 0xF>(ra); rb += dppf<0x124, 0xF>(rb);
;                     ra += dppf<0x128, 0xF>(ra); rb += dppf<0x128, 0xF>(rb);
;                     if ((g * 2 + u) > 0 && (lane & 15) == 0) sY[(g * 2 + u - 1) * 16 + rl] = rb;
;                     const f32x2v sa2 = {ra, ra}, v2 = {V[u], V[u]};
;                     S01 = __builtin_elementwise_fma(S01, w01, __builtin_elementwise_fma(sa2, b01, v2 * k01));
;                     S23 = __builtin_elementwise_fma(S23, w23, __builtin_elementwise_fma(sa2, b23, v2 * k23));
;                     f32x2v py = S01 * r01; py = __builtin_elementwise_fma(S23, r23, py);
;                     pyprev = py.x + py.y;
;                 }
	v_pk_mul_f32 v[114:115], v[46:47], v[70:71]
	v_pk_mul_f32 v[118:119], v[46:47], v[66:67]
	v_pk_fma_f32 v[114:115], v[48:49], v[72:73], v[114:115]
	v_pk_fma_f32 v[118:119], v[48:49], v[68:69], v[118:119]
	v_add_f32_e32 v116, v114, v115
	v_add_f32_e32 v132, v118, v119
	v_pk_mul_f32 v[120:121], v[82:83], v[110:111] op_sel_hi:[1,0]
	v_pk_mul_f32 v[122:123], v[84:85], v[110:111] op_sel_hi:[1,0]
	v_add_f32_dpp v116, v116, v116 quad_perm:[1,0,3,2] row_mask:0xf bank_mask:0xf bound_ctrl:1
	v_cndmask_b32_e64 v137, v129, v130, s[8:9]
	v_pk_fma_f32 v[124:125], v[46:47], v[74:75], v[120:121]
	v_pk_fma_f32 v[126:127], v[48:49], v[76:77], v[122:123]
	v_add_f32_dpp v116, v116, v116 quad_perm:[2,3,0,1] row_mask:0xf bank_mask:0xf bound_ctrl:1
	v_cndmask_b32_e64 v186, v130, v129, s[8:9]
	ds_read_b128 v[50:53], v212 offset:34304
	ds_read_b128 v[62:65], v212 offset:17920
	v_add_f32_dpp v116, v116, v116 row_ror:4 row_mask:0xf bank_mask:0xf bound_ctrl:1
	v_add_f32_dpp v187, v186, v137 quad_perm:[1,0,3,2] row_mask:0xf bank_mask:0xf bound_ctrl:1
	ds_read_b128 v[54:57], v212 offset:9728
	ds_read_b128 v[58:61], v212 offset:42496
	v_add_f32_dpp v116, v116, v116 row_ror:8 row_mask:0xf bank_mask:0xf bound_ctrl:1
	ds_read_b128 v[66:69], v212 offset:1536
	v_pk_fma_f32 v[46:47], v[116:117], v[78:79], v[124:125] op_sel_hi:[0,1,1]
	v_pk_fma_f32 v[48:49], v[116:117], v[80:81], v[126:127] op_sel_hi:[0,1,1]
	ds_read2st64_b32 v[112:113], v213 offset0:102 offset1:103
	s_waitcnt lgkmcnt(6)
	v_pk_mul_f32 v[114:115], v[46:47], v[90:91]
	v_pk_mul_f32 v[118:119], v[46:47], v[86:87]
	v_pk_fma_f32 v[114:115], v[48:49], v[92:93], v[114:115]
	v_pk_fma_f32 v[118:119], v[48:49], v[88:89], v[118:119]
	v_add_f32_e32 v116, v114, v115
	v_add_f32_e32 v133, v118, v119
	v_pk_mul_f32 v[120:121], v[102:103], v[110:111] op_sel:[0,1] op_sel_hi:[1,1]
	v_pk_mul_f32 v[122:123], v[104:105], v[110:111] op_sel:[0,1] op_sel_hi:[1,1]
	v_add_f32_dpp v116, v116, v116 quad_perm:[1,0,3,2] row_mask:0xf bank_mask:0xf bound_ctrl:1
	v_cndmask_b32_e64 v137, v131, v132, s[8:9]
	v_pk_fma_f32 v[124:125], v[46:47], v[94:95], v[120:121]
	v_pk_fma_f32 v[126:127], v[48:49], v[96:97], v[122:123]
	v_add_f32_dpp v116, v116, v116 quad_perm:[2,3,0,1] row_mask:0xf bank_mask:0xf bound_ctrl:1
	v_cndmask_b32_e64 v186, v132, v131, s[8:9]
	ds_read_b128 v[70:73], v212 offset:34560
	ds_read_b128 v[82:85], v212 offset:18176
	v_add_f32_dpp v116, v116, v116 row_ror:4 row_mask:0xf bank_mask:0xf bound_ctrl:1
	v_add_f32_dpp v188, v186, v137 quad_perm:[1,0,3,2] row_mask:0xf bank_mask:0xf bound_ctrl:1
	ds_read_b128 v[74:77], v212 offset:9984
	ds_read_b128 v[78:81], v212 offset:42752
	v_add_f32_dpp v116, v116, v116 row_ror:8 row_mask:0xf bank_mask:0xf bound_ctrl:1
	ds_read_b128 v[86:89], v212 offset:1792
	v_pk_fma_f32 v[46:47], v[116:117], v[98:99], v[124:125] op_sel_hi:[0,1,1]
	v_pk_fma_f32 v[48:49], v[116:117], v[100:101], v[126:127] op_sel_hi:[0,1,1]
	s_waitcnt lgkmcnt(5)
	v_pk_mul_f32 v[114:115], v[46:47], v[50:51]
	v_pk_mul_f32 v[118:119], v[46:47], v[106:107]
	v_pk_fma_f32 v[114:115], v[48:49], v[52:53], v[114:115]
	v_pk_fma_f32 v[118:119], v[48:49], v[108:109], v[118:119]
	v_add_f32_e32 v116, v114, v115
	v_add_f32_e32 v134, v118, v119
	v_pk_mul_f32 v[120:121], v[62:63], v[112:113] op_sel_hi:[1,0]
	v_pk_mul_f32 v[122:123], v[64:65], v[112:113] op_sel_hi:[1,0]
	v_add_f32_dpp v116, v116, v116 quad_perm:[1,0,3,2] row_mask:0xf bank_mask:0xf bound_ctrl:1
	v_cndmask_b32_e32 v137, v187, v188, vcc
	v_pk_fma_f32 v[124:125], v[46:47], v[54:55], v[120:121]
	v_pk_fma_f32 v[126:127], v[48:49], v[56:57], v[122:123]
	v_add_f32_dpp v116, v116, v116 quad_perm:[2,3,0,1] row_mask:0xf bank_mask:0xf bound_ctrl:1
	v_cndmask_b32_e32 v186, v188, v187, vcc
	ds_read_b128 v[90:93], v212 offset:34816
	ds_read_b128 v[102:105], v212 offset:18432
	v_add_f32_dpp v116, v116, v116 row_ror:4 row_mask:0xf bank_mask:0xf bound_ctrl:1
	v_add_f32_dpp v189, v186, v137 quad_perm:[2,3,0,1] row_mask:0xf bank_mask:0xf bound_ctrl:1
	ds_read_b128 v[94:97], v212 offset:10240
	ds_read_b128 v[98:101], v212 offset:43008
	v_add_f32_dpp v116, v116, v116 row_ror:8 row_mask:0xf bank_mask:0xf bound_ctrl:1
	ds_read_b128 v[106:109], v212 offset:2048
	v_pk_fma_f32 v[46:47], v[116:117], v[58:59], v[124:125] op_sel_hi:[0,1,1]
	v_pk_fma_f32 v[48:49], v[116:117], v[60:61], v[126:127] op_sel_hi:[0,1,1]
	ds_read2st64_b32 v[110:111], v213 offset0:104 offset1:105
	s_waitcnt lgkmcnt(6)
	v_pk_mul_f32 v[114:115], v[46:47], v[70:71]
	v_pk_mul_f32 v[118:119], v[46:47], v[66:67]
	v_pk_fma_f32 v[114:115], v[48:49], v[72:73], v[114:115]
	v_pk_fma_f32 v[118:119], v[48:49], v[68:69], v[118:119]
	v_add_f32_e32 v116, v114, v115
	v_add_f32_e32 v135, v118, v119
	v_pk_mul_f32 v[120:121], v[82:83], v[112:113] op_sel:[0,1] op_sel_hi:[1,1]
	v_pk_mul_f32 v[122:123], v[84:85], v[112:113] op_sel:[0,1] op_sel_hi:[1,1]
	v_add_f32_dpp v116, v116, v116 quad_perm:[1,0,3,2] row_mask:0xf bank_mask:0xf bound_ctrl:1
	v_add_f32_dpp v189, v189, v189 row_ror:4 row_mask:0xf bank_mask:0xf bound_ctrl:1
	v_pk_fma_f32 v[124:125], v[46:47], v[74:75], v[120:121]
	v_pk_fma_f32 v[126:127], v[48:49], v[76:77], v[122:123]
	v_add_f32_dpp v116, v116, v116 quad_perm:[2,3,0,1] row_mask:0xf bank_mask:0xf bound_ctrl:1
	v_add_f32_dpp v189, v189, v189 row_ror:8 row_mask:0xf bank_mask:0xf bound_ctrl:1
	ds_read_b128 v[50:53], v212 offset:35072
	ds_read_b128 v[62:65], v212 offset:18688
	v_add_f32_dpp v116, v116, v116 row_ror:4 row_mask:0xf bank_mask:0xf bound_ctrl:1
	ds_write_b32 v211, v189 offset:0
	ds_read_b128 v[54:57], v212 offset:10496
	ds_read_b128 v[58:61], v212 offset:43264
	v_add_f32_dpp v116, v116, v116 row_ror:8 row_mask:0xf bank_mask:0xf bound_ctrl:1
	ds_read_b128 v[66:69], v212 offset:2304
	v_pk_fma_f32 v[46:47], v[116:117], v[78:79], v[124:125] op_sel_hi:[0,1,1]
	v_pk_fma_f32 v[48:49], v[116:117], v[80:81], v[126:127] op_sel_hi:[0,1,1]
	s_waitcnt lgkmcnt(6)
; __device__ __forceinline__ void rwkv_prompt_unit(const Params& p, int l, int b, int h, int ibase, float* sf) {
;     ...
;             for (int g = 0; g < 16; ++g) {
;                 f32x4 Rn[2], Wn[2], Kn[2], An[2], Bn[2]; float Vn[2];
;                 if (g + 1 < 16) RW_LOAD(Rn, Wn, Kn, An, Bn, Vn, g + 1);
;                 __builtin_amdgcn_sched_barrier(0);
; #pragma unroll
;                 for (int u = 0; u < 2; ++u) {
;                     const f32x2v a01 = {A[u].x, A[u].y}, a23 = {A[u].z, A[u].w}, w01 = {W[u].x, W[u].y}, w23 = {W[u].z, W[u].w}, b01 = {B[u].x, B[u].y}, b23 = {B[u].z, B[u].w};
;                     const f32x2v k01 = {K[u].x, K[u].y}, k23 = {K[u].z, K[u].w}, r01 = {R[u].x, R[u].y}, r23 = {R[u].z, R[u].w};
;                     f32x2v pa = S01 * a01; pa = __builtin_elementwise_fma(S23, a23, pa);
;                     float ra = pa.x + pa.y, rb = pyprev;
;                     ra += dppf<0xB1, 0xF>(ra); rb += dppf<0xB1, 0xF>(rb);
;                     ra += dppf<0x4E, 0xF>(ra); rb += dppf<0x4E, 0xF>(rb);
;                     ra += dppf<0x124, 0xF>(ra); rb += dppf<0x124, 0xF>(rb);
;                     ra += dppf<0x128, 0xF>(ra); rb += dppf<0x128, 0xF>(rb);
;                     if ((g * 2 + u) > 0 && (lane & 15) == 0) sY[(g * 2 + u - 1) * 16 + rl] = rb;
;                     const f32x2v sa2 = {ra, ra}, v2 = {V[u], V[u]};
;                     S01 = __builtin_elementwise_fma(S01, w01, __builtin_elementwise_fma(sa2, b01, v2 * k01));
;                     S23 = __builtin_elementwise_fma(S23, w23, __builtin_elementwise_fma(sa2, b23, v2 * k23));
;                     f32x2v py = S01 * r01; py = __builtin_elementwise_fma(S23, r23, py);
;                     pyprev = py.x + py.y;
;                 }
	v_pk_mul_f32 v[114:115], v[46:47], v[90:91]
	v_pk_mul_f32 v[118:119], v[46:47], v[86:87]
	v_pk_fma_f32 v[114:115], v[48:49], v[92:93], v[114:115]
	v_pk_fma_f32 v[118:119], v[48:49], v[88:89], v[118:119]
	v_add_f32_e32 v116, v114, v115
	v_add_f32_e32 v136, v118, v119
	v_pk_mul_f32 v[120:121], v[102:103], v[110:111] op_sel_hi:[1,0]
	v_pk_mul_f32 v[122:123], v[104:105], v[110:111] op_sel_hi:[1,0]
	v_add_f32_dpp v116, v116, v116 quad_perm:[1,0,3,2] row_mask:0xf bank_mask:0xf bound_ctrl:1
	v_cndmask_b32_e64 v137, v133, v134, s[8:9]
	v_pk_fma_f32 v[124:125], v[46:47], v[94:95], v[120:121]
	v_pk_fma_f32 v[126:127], v[48:49], v[96:97], v[122:123]
	v_add_f32_dpp v116, v116, v116 quad_perm:[2,3,0,1] row_mask:0xf bank_mask:0xf bound_ctrl:1
	v_cndmask_b32_e64 v186, v134, v133, s[8:9]
	ds_read_b128 v[70:73], v212 offset:35328
	ds_read_b128 v[82:85], v212 offset:18944
	v_add_f32_dpp v116, v116, v116 row_ror:4 row_mask:0xf bank_mask:0xf bound_ctrl:1
	v_add_f32_dpp v187, v186, v137 quad_perm:[1,0,3,2] row_mask:0xf bank_mask:0xf bound_ctrl:1
	ds_read_b128 v[74:77], v212 offset:10752
	ds_read_b128 v[78:81], v212 offset:43520
	v_add_f32_dpp v116, v116, v116 row_ror:8 row_mask:0xf bank_mask:0xf bound_ctrl:1
	ds_read_b128 v[86:89], v212 offset:2560
	v_pk_fma_f32 v[46:47], v[116:117], v[98:99], v[124:125] op_sel_hi:[0,1,1]
	v_pk_fma_f32 v[48:49], v[116:117], v[100:101], v[126:127] op_sel_hi:[0,1,1]
	ds_read2st64_b32 v[112:113], v213 offset0:106 offset1:107
	s_waitcnt lgkmcnt(6)
	v_pk_mul_f32 v[114:115], v[46:47], v[50:51]
	v_pk_mul_f32 v[118:119], v[46:47], v[106:107]
	v_pk_fma_f32 v[114:115], v[48:49], v[52:53], v[114:115]
	v_pk_fma_f32 v[118:119], v[48:49], v[108:109], v[118:119]
	v_add_f32_e32 v116, v114, v115
	v_add_f32_e32 v129, v118, v119
	v_pk_mul_f32 v[120:121], v[62:63], v[110:111] op_sel:[0,1] op_sel_hi:[1,1]
	v_pk_mul_f32 v[122:123], v[64:65], v[110:111] op_sel:[0,1] op_sel_hi:[1,1]
	v_add_f32_dpp v116, v116, v116 quad_perm:[1,0,3,2] row_mask:0xf bank_mask:0xf bound_ctrl:1
	v_cndmask_b32_e64 v137, v135, v136, s[8:9]
	v_pk_fma_f32 v[124:125], v[46:47], v[54:55], v[120:121]
	v_pk_fma_f32 v[126:127], v[48:49], v[56:57], v[122:123]
	v_add_f32_dpp v116, v116, v116 quad_perm:[2,3,0,1] row_mask:0xf bank_mask:0xf bound_ctrl:1
	v_cndmask_b32_e64 v186, v136, v135, s[8:9]
	ds_read_b128 v[90:93], v212 offset:35584
	ds_read_b128 v[102:105], v212 offset:19200
	v_add_f32_dpp v116, v116, v116 row_ror:4 row_mask:0xf bank_mask:0xf bound_ctrl:1
	v_add_f32_dpp v188, v186, v137 quad_perm:[1,0,3,2] row_mask:0xf bank_mask:0xf bound_ctrl:1
	ds_read_b128 v[94:97], v212 offset:11008
	ds_read_b128 v[98:101], v212 offset:43776
	v_add_f32_dpp v116, v116, v116 row_ror:8 row_mask:0xf bank_mask:0xf bound_ctrl:1
	ds_read_b128 v[106:109], v212 offset:2816
	v_pk_fma_f32 v[46:47], v[116:117], v[58:59], v[124:125] op_sel_hi:[0,1,1]
	v_pk_fma_f32 v[48:49], v[116:117], v[60:61], v[126:127] op_sel_hi:[0,1,1]
	s_waitcnt lgkmcnt(5)
	v_pk_mul_f32 v[114:115], v[46:47], v[70:71]
	v_pk_mul_f32 v[118:119], v[46:47], v[66:67]
	v_pk_fma_f32 v[114:115], v[48:49], v[72:73], v[114:115]
	v_pk_fma_f32 v[118:119], v[48:49], v[68:69], v[118:119]
	v_add_f32_e32 v116, v114, v115
	v_add_f32_e32 v130, v118, v119
	v_pk_mul_f32 v[120:121], v[82:83], v[112:113] op_sel_hi:[1,0]
	v_pk_mul_f32 v[122:123], v[84:85], v[112:113] op_sel_hi:[1,0]
	v_add_f32_dpp v116, v116, v116 quad_perm:[1,0,3,2] row_mask:0xf bank_mask:0xf bound_ctrl:1
	v_cndmask_b32_e32 v137, v187, v188, vcc
	v_pk_fma_f32 v[124:125], v[46:47], v[74:75], v[120:121]
	v_pk_fma_f32 v[126:127], v[48:49], v[76:77], v[122:123]
	v_add_f32_dpp v116, v116, v116 quad_perm:[2,3,0,1] row_mask:0xf bank_mask:0xf bound_ctrl:1
	v_cndmask_b32_e32 v186, v188, v187, vcc
	ds_read_b128 v[50:53], v212 offset:35840
	ds_read_b128 v[62:65], v212 offset:19456
	v_add_f32_dpp v116, v116, v116 row_ror:4 row_mask:0xf bank_mask:0xf bound_ctrl:1
	v_add_f32_dpp v189, v186, v137 quad_perm:[2,3,0,1] row_mask:0xf bank_mask:0xf bound_ctrl:1
	ds_read_b128 v[54:57], v212 offset:11264
	ds_read_b128 v[58:61], v212 offset:44032
	v_add_f32_dpp v116, v116, v116 row_ror:8 row_mask:0xf bank_mask:0xf bound_ctrl:1
	ds_read_b128 v[66:69], v212 offset:3072
	v_pk_fma_f32 v[46:47], v[116:117], v[78:79], v[124:125] op_sel_hi:[0,1,1]
	v_pk_fma_f32 v[48:49], v[116:117], v[80:81], v[126:127] op_sel_hi:[0,1,1]
	ds_read2st64_b32 v[110:111], v213 offset0:108 offset1:109
	s_waitcnt lgkmcnt(6)
	v_pk_mul_f32 v[114:115], v[46:47], v[90:91]
	v_pk_mul_f32 v[118:119], v[46:47], v[86:87]
	v_pk_fma_f32 v[114:115], v[48:49], v[92:93], v[114:115]
	v_pk_fma_f32 v[118:119], v[48:49], v[88:89], v[118:119]
	v_add_f32_e32 v116, v114, v115
	v_add_f32_e32 v131, v118, v119
	v_pk_mul_f32 v[120:121], v[102:103], v[112:113] op_sel:[0,1] op_sel_hi:[1,1]
	v_pk_mul_f32 v[122:123], v[104:105], v[112:113] op_sel:[0,1] op_sel_hi:[1,1]
	v_add_f32_dpp v116, v116, v116 quad_perm:[1,0,3,2] row_mask:0xf bank_mask:0xf bound_ctrl:1
	v_add_f32_dpp v189, v189, v189 row_ror:4 row_mask:0xf bank_mask:0xf bound_ctrl:1
	v_pk_fma_f32 v[124:125], v[46:47], v[94:95], v[120:121]
	v_pk_fma_f32 v[126:127], v[48:49], v[96:97], v[122:123]
	v_add_f32_dpp v116, v116, v116 quad_perm:[2,3,0,1] row_mask:0xf bank_mask:0xf bound_ctrl:1
	v_add_f32_dpp v189, v189, v189 row_ror:8 row_mask:0xf bank_mask:0xf bound_ctrl:1
	ds_read_b128 v[70:73], v212 offset:36096
	ds_read_b128 v[82:85], v212 offset:19712
	v_add_f32_dpp v116, v116, v116 row_ror:4 row_mask:0xf bank_mask:0xf bound_ctrl:1
	ds_write_b32 v211, v189 offset:256
	ds_read_b128 v[74:77], v212 offset:11520
	ds_read_b128 v[78:81], v212 offset:44288
	v_add_f32_dpp v116, v116, v116 row_ror:8 row_mask:0xf bank_mask:0xf bound_ctrl:1
	ds_read_b128 v[86:89], v212 offset:3328
	v_pk_fma_f32 v[46:47], v[116:117], v[98:99], v[124:125] op_sel_hi:[0,1,1]
	v_pk_fma_f32 v[48:49], v[116:117], v[100:101], v[126:127] op_sel_hi:[0,1,1]
	s_waitcnt lgkmcnt(6)
; __device__ __forceinline__ void rwkv_prompt_unit(const Params& p, int l, int b, int h, int ibase, float* sf) {
;     ...
;             for (int g = 0; g < 16; ++g) {
;                 f32x4 Rn[2], Wn[2], Kn[2], An[2], Bn[2]; float Vn[2];
;                 if (g + 1 < 16) RW_LOAD(Rn, Wn, Kn, An, Bn, Vn, g + 1);
;                 __builtin_amdgcn_sched_barrier(0);
; #pragma unroll
;                 for (int u = 0; u < 2; ++u) {
;                     const f32x2v a01 = {A[u].x, A[u].y}, a23 = {A[u].z, A[u].w}, w01 = {W[u].x, W[u].y}, w23 = {W[u].z, W[u].w}, b01 = {B[u].x, B[u].y}, b23 = {B[u].z, B[u].w};
;                     const f32x2v k01 = {K[u].x, K[u].y}, k23 = {K[u].z, K[u].w}, r01 = {R[u].x, R[u].y}, r23 = {R[u].z, R[u].w};
;                     f32x2v pa = S01 * a01; pa = __builtin_elementwise_fma(S23, a23, pa);
;                     float ra = pa.x + pa.y, rb = pyprev;
;                     ra += dppf<0xB1, 0xF>(ra); rb += dppf<0xB1, 0xF>(rb);
;                     ra += dppf<0x4E, 0xF>(ra); rb += dppf<0x4E, 0xF>(rb);
;                     ra += dppf<0x124, 0xF>(ra); rb += dppf<0x124, 0xF>(rb);
;                     ra += dppf<0x128, 0xF>(ra); rb += dppf<0x128, 0xF>(rb);
;                     if ((g * 2 + u) > 0 && (lane & 15) == 0) sY[(g * 2 + u - 1) * 16 + rl] = rb;
;                     const f32x2v sa2 = {ra, ra}, v2 = {V[u], V[u]};
;                     S01 = __builtin_elementwise_fma(S01, w01, __builtin_elementwise_fma(sa2, b01, v2 * k01));
;                     S23 = __builtin_elementwise_fma(S23, w23, __builtin_elementwise_fma(sa2, b23, v2 * k23));
;                     f32x2v py = S01 * r01; py = __builtin_elementwise_fma(S23, r23, py);
;                     pyprev = py.x + py.y;
;                 }
	v_pk_mul_f32 v[114:115], v[46:47], v[50:51]
	v_pk_mul_f32 v[118:119], v[46:47], v[106:107]
	v_pk_fma_f32 v[114:115], v[48:49], v[52:53], v[114:115]
	v_pk_fma_f32 v[118:119], v[48:49], v[108:109], v[118:119]
	v_add_f32_e32 v116, v114, v115
	v_add_f32_e32 v132, v118, v119
	v_pk_mul_f32 v[120:121], v[62:63], v[110:111] op_sel_hi:[1,0]
	v_pk_mul_f32 v[122:123], v[64:65], v[110:111] op_sel_hi:[1,0]
	v_add_f32_dpp v116, v116, v116 quad_perm:[1,0,3,2] row_mask:0xf bank_mask:0xf bound_ctrl:1
	v_cndmask_b32_e64 v137, v129, v130, s[8:9]
	v_pk_fma_f32 v[124:125], v[46:47], v[54:55], v[120:121]
	v_pk_fma_f32 v[126:127], v[48:49], v[56:57], v[122:123]
	v_add_f32_dpp v116, v116, v116 quad_perm:[2,3,0,1] row_mask:0xf bank_mask:0xf bound_ctrl:1
	v_cndmask_b32_e64 v186, v130, v129, s[8:9]
	ds_read_b128 v[90:93], v212 offset:36352
	ds_read_b128 v[102:105], v212 offset:19968
	v_add_f32_dpp v116, v116, v116 row_ror:4 row_mask:0xf bank_mask:0xf bound_ctrl:1
	v_add_f32_dpp v187, v186, v137 quad_perm:[1,0,3,2] row_mask:0xf bank_mask:0xf bound_ctrl:1
	ds_read_b128 v[94:97], v212 offset:11776
	ds_read_b128 v[98:101], v212 offset:44544
	v_add_f32_dpp v116, v116, v116 row_ror:8 row_mask:0xf bank_mask:0xf bound_ctrl:1
	ds_read_b128 v[106:109], v212 offset:3584
	v_pk_fma_f32 v[46:47], v[116:117], v[58:59], v[124:125] op_sel_hi:[0,1,1]
	v_pk_fma_f32 v[48:49], v[116:117], v[60:61], v[126:127] op_sel_hi:[0,1,1]
	ds_read2st64_b32 v[112:113], v213 offset0:110 offset1:111
	s_waitcnt lgkmcnt(6)
	v_pk_mul_f32 v[114:115], v[46:47], v[70:71]
	v_pk_mul_f32 v[118:119], v[46:47], v[66:67]
	v_pk_fma_f32 v[114:115], v[48:49], v[72:73], v[114:115]
	v_pk_fma_f32 v[118:119], v[48:49], v[68:69], v[118:119]
	v_add_f32_e32 v116, v114, v115
	v_add_f32_e32 v133, v118, v119
	v_pk_mul_f32 v[120:121], v[82:83], v[110:111] op_sel:[0,1] op_sel_hi:[1,1]
	v_pk_mul_f32 v[122:123], v[84:85], v[110:111] op_sel:[0,1] op_sel_hi:[1,1]
	v_add_f32_dpp v116, v116, v116 quad_perm:[1,0,3,2] row_mask:0xf bank_mask:0xf bound_ctrl:1
	v_cndmask_b32_e64 v137, v131, v132, s[8:9]
	v_pk_fma_f32 v[124:125], v[46:47], v[74:75], v[120:121]
	v_pk_fma_f32 v[126:127], v[48:49], v[76:77], v[122:123]
	v_add_f32_dpp v116, v116, v116 quad_perm:[2,3,0,1] row_mask:0xf bank_mask:0xf bound_ctrl:1
	v_cndmask_b32_e64 v186, v132, v131, s[8:9]
	ds_read_b128 v[50:53], v212 offset:36608
	ds_read_b128 v[62:65], v212 offset:20224
	v_add_f32_dpp v116, v116, v116 row_ror:4 row_mask:0xf bank_mask:0xf bound_ctrl:1
	v_add_f32_dpp v188, v186, v137 quad_perm:[1,0,3,2] row_mask:0xf bank_mask:0xf bound_ctrl:1
	ds_read_b128 v[54:57], v212 offset:12032
	ds_read_b128 v[58:61], v212 offset:44800
	v_add_f32_dpp v116, v116, v116 row_ror:8 row_mask:0xf bank_mask:0xf bound_ctrl:1
	ds_read_b128 v[66:69], v212 offset:3840
	v_pk_fma_f32 v[46:47], v[116:117], v[78:79], v[124:125] op_sel_hi:[0,1,1]
	v_pk_fma_f32 v[48:49], v[116:117], v[80:81], v[126:127] op_sel_hi:[0,1,1]
	s_waitcnt lgkmcnt(5)
	v_pk_mul_f32 v[114:115], v[46:47], v[90:91]
	v_pk_mul_f32 v[118:119], v[46:47], v[86:87]
	v_pk_fma_f32 v[114:115], v[48:49], v[92:93], v[114:115]
	v_pk_fma_f32 v[118:119], v[48:49], v[88:89], v[118:119]
	v_add_f32_e32 v116, v114, v115
	v_add_f32_e32 v134, v118, v119
	v_pk_mul_f32 v[120:121], v[102:103], v[112:113] op_sel_hi:[1,0]
	v_pk_mul_f32 v[122:123], v[104:105], v[112:113] op_sel_hi:[1,0]
	v_add_f32_dpp v116, v116, v116 quad_perm:[1,0,3,2] row_mask:0xf bank_mask:0xf bound_ctrl:1
	v_cndmask_b32_e32 v137, v187, v188, vcc
	v_pk_fma_f32 v[124:125], v[46:47], v[94:95], v[120:121]
	v_pk_fma_f32 v[126:127], v[48:49], v[96:97], v[122:123]
	v_add_f32_dpp v116, v116, v116 quad_perm:[2,3,0,1] row_mask:0xf bank_mask:0xf bound_ctrl:1
	v_cndmask_b32_e32 v186, v188, v187, vcc
	ds_read_b128 v[70:73], v212 offset:36864
	ds_read_b128 v[82:85], v212 offset:20480
	v_add_f32_dpp v116, v116, v116 row_ror:4 row_mask:0xf bank_mask:0xf bound_ctrl:1
	v_add_f32_dpp v189, v186, v137 quad_perm:[2,3,0,1] row_mask:0xf bank_mask:0xf bound_ctrl:1
	ds_read_b128 v[74:77], v212 offset:12288
	ds_read_b128 v[78:81], v212 offset:45056
	v_add_f32_dpp v116, v116, v116 row_ror:8 row_mask:0xf bank_mask:0xf bound_ctrl:1
	ds_read_b128 v[86:89], v212 offset:4096
	v_pk_fma_f32 v[46:47], v[116:117], v[98:99], v[124:125] op_sel_hi:[0,1,1]
	v_pk_fma_f32 v[48:49], v[116:117], v[100:101], v[126:127] op_sel_hi:[0,1,1]
	ds_read2st64_b32 v[110:111], v213 offset0:112 offset1:113
	s_waitcnt lgkmcnt(6)
	v_pk_mul_f32 v[114:115], v[46:47], v[50:51]
	v_pk_mul_f32 v[118:119], v[46:47], v[106:107]
	v_pk_fma_f32 v[114:115], v[48:49], v[52:53], v[114:115]
	v_pk_fma_f32 v[118:119], v[48:49], v[108:109], v[118:119]
	v_add_f32_e32 v116, v114, v115
	v_add_f32_e32 v135, v118, v119
	v_pk_mul_f32 v[120:121], v[62:63], v[112:113] op_sel:[0,1] op_sel_hi:[1,1]
	v_pk_mul_f32 v[122:123], v[64:65], v[112:113] op_sel:[0,1] op_sel_hi:[1,1]
	v_add_f32_dpp v116, v116, v116 quad_perm:[1,0,3,2] row_mask:0xf bank_mask:0xf bound_ctrl:1
	v_add_f32_dpp v189, v189, v189 row_ror:4 row_mask:0xf bank_mask:0xf bound_ctrl:1
	v_pk_fma_f32 v[124:125], v[46:47], v[54:55], v[120:121]
	v_pk_fma_f32 v[126:127], v[48:49], v[56:57], v[122:123]
	v_add_f32_dpp v116, v116, v116 quad_perm:[2,3,0,1] row_mask:0xf bank_mask:0xf bound_ctrl:1
	v_add_f32_dpp v189, v189, v189 row_ror:8 row_mask:0xf bank_mask:0xf bound_ctrl:1
	ds_read_b128 v[90:93], v212 offset:37120
	ds_read_b128 v[102:105], v212 offset:20736
	v_add_f32_dpp v116, v116, v116 row_ror:4 row_mask:0xf bank_mask:0xf bound_ctrl:1
	ds_write_b32 v211, v189 offset:512
	ds_read_b128 v[94:97], v212 offset:12544
	ds_read_b128 v[98:101], v212 offset:45312
	v_add_f32_dpp v116, v116, v116 row_ror:8 row_mask:0xf bank_mask:0xf bound_ctrl:1
	ds_read_b128 v[106:109], v212 offset:4352
	v_pk_fma_f32 v[46:47], v[116:117], v[58:59], v[124:125] op_sel_hi:[0,1,1]
	v_pk_fma_f32 v[48:49], v[116:117], v[60:61], v[126:127] op_sel_hi:[0,1,1]
	s_waitcnt lgkmcnt(6)
; __device__ __forceinline__ void rwkv_prompt_unit(const Params& p, int l, int b, int h, int ibase, float* sf) {
;     ...
;             for (int g = 0; g < 16; ++g) {
;                 f32x4 Rn[2], Wn[2], Kn[2], An[2], Bn[2]; float Vn[2];
;                 if (g + 1 < 16) RW_LOAD(Rn, Wn, Kn, An, Bn, Vn, g + 1);
;                 __builtin_amdgcn_sched_barrier(0);
; #pragma unroll
;                 for (int u = 0; u < 2; ++u) {
;                     const f32x2v a01 = {A[u].x, A[u].y}, a23 = {A[u].z, A[u].w}, w01 = {W[u].x, W[u].y}, w23 = {W[u].z, W[u].w}, b01 = {B[u].x, B[u].y}, b23 = {B[u].z, B[u].w};
;                     const f32x2v k01 = {K[u].x, K[u].y}, k23 = {K[u].z, K[u].w}, r01 = {R[u].x, R[u].y}, r23 = {R[u].z, R[u].w};
;                     f32x2v pa = S01 * a01; pa = __builtin_elementwise_fma(S23, a23, pa);
;                     float ra = pa.x + pa.y, rb = pyprev;
;                     ra += dppf<0xB1, 0xF>(ra); rb += dppf<0xB1, 0xF>(rb);
;                     ra += dppf<0x4E, 0xF>(ra); rb += dppf<0x4E, 0xF>(rb);
;                     ra += dppf<0x124, 0xF>(ra); rb += dppf<0x124, 0xF>(rb);
;                     ra += dppf<0x128, 0xF>(ra); rb += dppf<0x128, 0xF>(rb);
;                     if ((g * 2 + u) > 0 && (lane & 15) == 0) sY[(g * 2 + u - 1) * 16 + rl] = rb;
;                     const f32x2v sa2 = {ra, ra}, v2 = {V[u], V[u]};
;                     S01 = __builtin_elementwise_fma(S01, w01, __builtin_elementwise_fma(sa2, b01, v2 * k01));
;                     S23 = __builtin_elementwise_fma(S23, w23, __builtin_elementwise_fma(sa2, b23, v2 * k23));
;                     f32x2v py = S01 * r01; py = __builtin_elementwise_fma(S23, r23, py);
;                     pyprev = py.x + py.y;
;                 }
	v_pk_mul_f32 v[114:115], v[46:47], v[70:71]
	v_pk_mul_f32 v[118:119], v[46:47], v[66:67]
	v_pk_fma_f32 v[114:115], v[48:49], v[72:73], v[114:115]
	v_pk_fma_f32 v[118:119], v[48:49], v[68:69], v[118:119]
	v_add_f32_e32 v116, v114, v115
	v_add_f32_e32 v136, v118, v119
	v_pk_mul_f32 v[120:121], v[82:83], v[110:111] op_sel_hi:[1,0]
	v_pk_mul_f32 v[122:123], v[84:85], v[110:111] op_sel_hi:[1,0]
	v_add_f32_dpp v116, v116, v116 quad_perm:[1,0,3,2] row_mask:0xf bank_mask:0xf bound_ctrl:1
	v_cndmask_b32_e64 v137, v133, v134, s[8:9]
	v_pk_fma_f32 v[124:125], v[46:47], v[74:75], v[120:121]
	v_pk_fma_f32 v[126:127], v[48:49], v[76:77], v[122:123]
	v_add_f32_dpp v116, v116, v116 quad_perm:[2,3,0,1] row_mask:0xf bank_mask:0xf bound_ctrl:1
	v_cndmask_b32_e64 v186, v134, v133, s[8:9]
	ds_read_b128 v[50:53], v212 offset:37376
	ds_read_b128 v[62:65], v212 offset:20992
	v_add_f32_dpp v116, v116, v116 row_ror:4 row_mask:0xf bank_mask:0xf bound_ctrl:1
	v_add_f32_dpp v187, v186, v137 quad_perm:[1,0,3,2] row_mask:0xf bank_mask:0xf bound_ctrl:1
	ds_read_b128 v[54:57], v212 offset:12800
	ds_read_b128 v[58:61], v212 offset:45568
	v_add_f32_dpp v116, v116, v116 row_ror:8 row_mask:0xf bank_mask:0xf bound_ctrl:1
	ds_read_b128 v[66:69], v212 offset:4608
	v_pk_fma_f32 v[46:47], v[116:117], v[78:79], v[124:125] op_sel_hi:[0,1,1]
	v_pk_fma_f32 v[48:49], v[116:117], v[80:81], v[126:127] op_sel_hi:[0,1,1]
	ds_read2st64_b32 v[112:113], v213 offset0:114 offset1:115
	s_waitcnt lgkmcnt(6)
	v_pk_mul_f32 v[114:115], v[46:47], v[90:91]
	v_pk_mul_f32 v[118:119], v[46:47], v[86:87]
	v_pk_fma_f32 v[114:115], v[48:49], v[92:93], v[114:115]
	v_pk_fma_f32 v[118:119], v[48:49], v[88:89], v[118:119]
	v_add_f32_e32 v116, v114, v115
	v_add_f32_e32 v129, v118, v119
	v_pk_mul_f32 v[120:121], v[102:103], v[110:111] op_sel:[0,1] op_sel_hi:[1,1]
	v_pk_mul_f32 v[122:123], v[104:105], v[110:111] op_sel:[0,1] op_sel_hi:[1,1]
	v_add_f32_dpp v116, v116, v116 quad_perm:[1,0,3,2] row_mask:0xf bank_mask:0xf bound_ctrl:1
	v_cndmask_b32_e64 v137, v135, v136, s[8:9]
	v_pk_fma_f32 v[124:125], v[46:47], v[94:95], v[120:121]
	v_pk_fma_f32 v[126:127], v[48:49], v[96:97], v[122:123]
	v_add_f32_dpp v116, v116, v116 quad_perm:[2,3,0,1] row_mask:0xf bank_mask:0xf bound_ctrl:1
	v_cndmask_b32_e64 v186, v136, v135, s[8:9]
	ds_read_b128 v[70:73], v212 offset:37632
	ds_read_b128 v[82:85], v212 offset:21248
	v_add_f32_dpp v116, v116, v116 row_ror:4 row_mask:0xf bank_mask:0xf bound_ctrl:1
	v_add_f32_dpp v188, v186, v137 quad_perm:[1,0,3,2] row_mask:0xf bank_mask:0xf bound_ctrl:1
	ds_read_b128 v[74:77], v212 offset:13056
	ds_read_b128 v[78:81], v212 offset:45824
	v_add_f32_dpp v116, v116, v116 row_ror:8 row_mask:0xf bank_mask:0xf bound_ctrl:1
	ds_read_b128 v[86:89], v212 offset:4864
	v_pk_fma_f32 v[46:47], v[116:117], v[98:99], v[124:125] op_sel_hi:[0,1,1]
	v_pk_fma_f32 v[48:49], v[116:117], v[100:101], v[126:127] op_sel_hi:[0,1,1]
	s_waitcnt lgkmcnt(5)
	v_pk_mul_f32 v[114:115], v[46:47], v[50:51]
	v_pk_mul_f32 v[118:119], v[46:47], v[106:107]
	v_pk_fma_f32 v[114:115], v[48:49], v[52:53], v[114:115]
	v_pk_fma_f32 v[118:119], v[48:49], v[108:109], v[118:119]
	v_add_f32_e32 v116, v114, v115
	v_add_f32_e32 v130, v118, v119
	v_pk_mul_f32 v[120:121], v[62:63], v[112:113] op_sel_hi:[1,0]
	v_pk_mul_f32 v[122:123], v[64:65], v[112:113] op_sel_hi:[1,0]
	v_add_f32_dpp v116, v116, v116 quad_perm:[1,0,3,2] row_mask:0xf bank_mask:0xf bound_ctrl:1
	v_cndmask_b32_e32 v137, v187, v188, vcc
	v_pk_fma_f32 v[124:125], v[46:47], v[54:55], v[120:121]
	v_pk_fma_f32 v[126:127], v[48:49], v[56:57], v[122:123]
	v_add_f32_dpp v116, v116, v116 quad_perm:[2,3,0,1] row_mask:0xf bank_mask:0xf bound_ctrl:1
	v_cndmask_b32_e32 v186, v188, v187, vcc
	ds_read_b128 v[90:93], v212 offset:37888
	ds_read_b128 v[102:105], v212 offset:21504
	v_add_f32_dpp v116, v116, v116 row_ror:4 row_mask:0xf bank_mask:0xf bound_ctrl:1
	v_add_f32_dpp v189, v186, v137 quad_perm:[2,3,0,1] row_mask:0xf bank_mask:0xf bound_ctrl:1
	ds_read_b128 v[94:97], v212 offset:13312
	ds_read_b128 v[98:101], v212 offset:46080
	v_add_f32_dpp v116, v116, v116 row_ror:8 row_mask:0xf bank_mask:0xf bound_ctrl:1
	ds_read_b128 v[106:109], v212 offset:5120
	v_pk_fma_f32 v[46:47], v[116:117], v[58:59], v[124:125] op_sel_hi:[0,1,1]
	v_pk_fma_f32 v[48:49], v[116:117], v[60:61], v[126:127] op_sel_hi:[0,1,1]
	ds_read2st64_b32 v[110:111], v213 offset0:116 offset1:117
	s_waitcnt lgkmcnt(6)
	v_pk_mul_f32 v[114:115], v[46:47], v[70:71]
	v_pk_mul_f32 v[118:119], v[46:47], v[66:67]
	v_pk_fma_f32 v[114:115], v[48:49], v[72:73], v[114:115]
	v_pk_fma_f32 v[118:119], v[48:49], v[68:69], v[118:119]
	v_add_f32_e32 v116, v114, v115
	v_add_f32_e32 v131, v118, v119
	v_pk_mul_f32 v[120:121], v[82:83], v[112:113] op_sel:[0,1] op_sel_hi:[1,1]
	v_pk_mul_f32 v[122:123], v[84:85], v[112:113] op_sel:[0,1] op_sel_hi:[1,1]
	v_add_f32_dpp v116, v116, v116 quad_perm:[1,0,3,2] row_mask:0xf bank_mask:0xf bound_ctrl:1
	v_add_f32_dpp v189, v189, v189 row_ror:4 row_mask:0xf bank_mask:0xf bound_ctrl:1
	v_pk_fma_f32 v[124:125], v[46:47], v[74:75], v[120:121]
	v_pk_fma_f32 v[126:127], v[48:49], v[76:77], v[122:123]
	v_add_f32_dpp v116, v116, v116 quad_perm:[2,3,0,1] row_mask:0xf bank_mask:0xf bound_ctrl:1
	v_add_f32_dpp v189, v189, v189 row_ror:8 row_mask:0xf bank_mask:0xf bound_ctrl:1
	ds_read_b128 v[50:53], v212 offset:38144
	ds_read_b128 v[62:65], v212 offset:21760
	v_add_f32_dpp v116, v116, v116 row_ror:4 row_mask:0xf bank_mask:0xf bound_ctrl:1
	ds_write_b32 v211, v189 offset:768
	ds_read_b128 v[54:57], v212 offset:13568
	ds_read_b128 v[58:61], v212 offset:46336
	v_add_f32_dpp v116, v116, v116 row_ror:8 row_mask:0xf bank_mask:0xf bound_ctrl:1
	ds_read_b128 v[66:69], v212 offset:5376
	v_pk_fma_f32 v[46:47], v[116:117], v[78:79], v[124:125] op_sel_hi:[0,1,1]
	v_pk_fma_f32 v[48:49], v[116:117], v[80:81], v[126:127] op_sel_hi:[0,1,1]
	s_waitcnt lgkmcnt(6)
; __device__ __forceinline__ void rwkv_prompt_unit(const Params& p, int l, int b, int h, int ibase, float* sf) {
;     ...
;             for (int g = 0; g < 16; ++g) {
;                 f32x4 Rn[2], Wn[2], Kn[2], An[2], Bn[2]; float Vn[2];
;                 if (g + 1 < 16) RW_LOAD(Rn, Wn, Kn, An, Bn, Vn, g + 1);
;                 __builtin_amdgcn_sched_barrier(0);
; #pragma unroll
;                 for (int u = 0; u < 2; ++u) {
;                     const f32x2v a01 = {A[u].x, A[u].y}, a23 = {A[u].z, A[u].w}, w01 = {W[u].x, W[u].y}, w23 = {W[u].z, W[u].w}, b01 = {B[u].x, B[u].y}, b23 = {B[u].z, B[u].w};
;                     const f32x2v k01 = {K[u].x, K[u].y}, k23 = {K[u].z, K[u].w}, r01 = {R[u].x, R[u].y}, r23 = {R[u].z, R[u].w};
;                     f32x2v pa = S01 * a01; pa = __builtin_elementwise_fma(S23, a23, pa);
;                     float ra = pa.x + pa.y, rb = pyprev;
;                     ra += dppf<0xB1, 0xF>(ra); rb += dppf<0xB1, 0xF>(rb);
;                     ra += dppf<0x4E, 0xF>(ra); rb += dppf<0x4E, 0xF>(rb);
;                     ra += dppf<0x124, 0xF>(ra); rb += dppf<0x124, 0xF>(rb);
;                     ra += dppf<0x128, 0xF>(ra); rb += dppf<0x128, 0xF>(rb);
;                     if ((g * 2 + u) > 0 && (lane & 15) == 0) sY[(g * 2 + u - 1) * 16 + rl] = rb;
;                     const f32x2v sa2 = {ra, ra}, v2 = {V[u], V[u]};
;                     S01 = __builtin_elementwise_fma(S01, w01, __builtin_elementwise_fma(sa2, b01, v2 * k01));
;                     S23 = __builtin_elementwise_fma(S23, w23, __builtin_elementwise_fma(sa2, b23, v2 * k23));
;                     f32x2v py = S01 * r01; py = __builtin_elementwise_fma(S23, r23, py);
;                     pyprev = py.x + py.y;
;                 }
;                 __builtin_amdgcn_sched_barrier(0);
;                 if (g + 1 < 16) {
; #pragma unroll
;                     for (int u = 0; u < 2; ++u) { R[u] = Rn[u]; W[u] = Wn[u]; K[u] = Kn[u]; A[u] = An[u]; B[u] = Bn[u]; V[u] = Vn[u]; }
;                 }
;             }
	v_pk_mul_f32 v[114:115], v[46:47], v[90:91]
	v_pk_mul_f32 v[118:119], v[46:47], v[86:87]
	v_pk_fma_f32 v[114:115], v[48:49], v[92:93], v[114:115]
	v_pk_fma_f32 v[118:119], v[48:49], v[88:89], v[118:119]
	v_add_f32_e32 v116, v114, v115
	v_add_f32_e32 v132, v118, v119
	v_pk_mul_f32 v[120:121], v[102:103], v[110:111] op_sel_hi:[1,0]
	v_pk_mul_f32 v[122:123], v[104:105], v[110:111] op_sel_hi:[1,0]
	v_add_f32_dpp v116, v116, v116 quad_perm:[1,0,3,2] row_mask:0xf bank_mask:0xf bound_ctrl:1
	v_cndmask_b32_e64 v137, v129, v130, s[8:9]
	v_pk_fma_f32 v[124:125], v[46:47], v[94:95], v[120:121]
	v_pk_fma_f32 v[126:127], v[48:49], v[96:97], v[122:123]
	v_add_f32_dpp v116, v116, v116 quad_perm:[2,3,0,1] row_mask:0xf bank_mask:0xf bound_ctrl:1
	v_cndmask_b32_e64 v186, v130, v129, s[8:9]
	ds_read_b128 v[70:73], v212 offset:38400
	ds_read_b128 v[82:85], v212 offset:22016
	v_add_f32_dpp v116, v116, v116 row_ror:4 row_mask:0xf bank_mask:0xf bound_ctrl:1
	v_add_f32_dpp v187, v186, v137 quad_perm:[1,0,3,2] row_mask:0xf bank_mask:0xf bound_ctrl:1
	ds_read_b128 v[74:77], v212 offset:13824
	ds_read_b128 v[78:81], v212 offset:46592
	v_add_f32_dpp v116, v116, v116 row_ror:8 row_mask:0xf bank_mask:0xf bound_ctrl:1
	ds_read_b128 v[86:89], v212 offset:5632
	v_pk_fma_f32 v[46:47], v[116:117], v[98:99], v[124:125] op_sel_hi:[0,1,1]
	v_pk_fma_f32 v[48:49], v[116:117], v[100:101], v[126:127] op_sel_hi:[0,1,1]
	ds_read2st64_b32 v[112:113], v213 offset0:118 offset1:119
	s_waitcnt lgkmcnt(6)
	v_pk_mul_f32 v[114:115], v[46:47], v[50:51]
	v_pk_mul_f32 v[118:119], v[46:47], v[106:107]
	v_pk_fma_f32 v[114:115], v[48:49], v[52:53], v[114:115]
	v_pk_fma_f32 v[118:119], v[48:49], v[108:109], v[118:119]
	v_add_f32_e32 v116, v114, v115
	v_add_f32_e32 v133, v118, v119
	v_pk_mul_f32 v[120:121], v[62:63], v[110:111] op_sel:[0,1] op_sel_hi:[1,1]
	v_pk_mul_f32 v[122:123], v[64:65], v[110:111] op_sel:[0,1] op_sel_hi:[1,1]
	v_add_f32_dpp v116, v116, v116 quad_perm:[1,0,3,2] row_mask:0xf bank_mask:0xf bound_ctrl:1
	v_cndmask_b32_e64 v137, v131, v132, s[8:9]
	v_pk_fma_f32 v[124:125], v[46:47], v[54:55], v[120:121]
	v_pk_fma_f32 v[126:127], v[48:49], v[56:57], v[122:123]
	v_add_f32_dpp v116, v116, v116 quad_perm:[2,3,0,1] row_mask:0xf bank_mask:0xf bound_ctrl:1
	v_cndmask_b32_e64 v186, v132, v131, s[8:9]
	ds_read_b128 v[90:93], v212 offset:38656
	ds_read_b128 v[102:105], v212 offset:22272
	v_add_f32_dpp v116, v116, v116 row_ror:4 row_mask:0xf bank_mask:0xf bound_ctrl:1
	v_add_f32_dpp v188, v186, v137 quad_perm:[1,0,3,2] row_mask:0xf bank_mask:0xf bound_ctrl:1
	ds_read_b128 v[94:97], v212 offset:14080
	ds_read_b128 v[98:101], v212 offset:46848
	v_add_f32_dpp v116, v116, v116 row_ror:8 row_mask:0xf bank_mask:0xf bound_ctrl:1
	ds_read_b128 v[106:109], v212 offset:5888
	v_pk_fma_f32 v[46:47], v[116:117], v[58:59], v[124:125] op_sel_hi:[0,1,1]
	v_pk_fma_f32 v[48:49], v[116:117], v[60:61], v[126:127] op_sel_hi:[0,1,1]
	s_waitcnt lgkmcnt(5)
	v_pk_mul_f32 v[114:115], v[46:47], v[70:71]
	v_pk_mul_f32 v[118:119], v[46:47], v[66:67]
	v_pk_fma_f32 v[114:115], v[48:49], v[72:73], v[114:115]
	v_pk_fma_f32 v[118:119], v[48:49], v[68:69], v[118:119]
	v_add_f32_e32 v116, v114, v115
	v_add_f32_e32 v134, v118, v119
	v_pk_mul_f32 v[120:121], v[82:83], v[112:113] op_sel_hi:[1,0]
	v_pk_mul_f32 v[122:123], v[84:85], v[112:113] op_sel_hi:[1,0]
	v_add_f32_dpp v116, v116, v116 quad_perm:[1,0,3,2] row_mask:0xf bank_mask:0xf bound_ctrl:1
	v_cndmask_b32_e32 v137, v187, v188, vcc
	v_pk_fma_f32 v[124:125], v[46:47], v[74:75], v[120:121]
	v_pk_fma_f32 v[126:127], v[48:49], v[76:77], v[122:123]
	v_add_f32_dpp v116, v116, v116 quad_perm:[2,3,0,1] row_mask:0xf bank_mask:0xf bound_ctrl:1
	v_cndmask_b32_e32 v186, v188, v187, vcc
	ds_read_b128 v[50:53], v212 offset:38912
	ds_read_b128 v[62:65], v212 offset:22528
	v_add_f32_dpp v116, v116, v116 row_ror:4 row_mask:0xf bank_mask:0xf bound_ctrl:1
	v_add_f32_dpp v189, v186, v137 quad_perm:[2,3,0,1] row_mask:0xf bank_mask:0xf bound_ctrl:1
	ds_read_b128 v[54:57], v212 offset:14336
	ds_read_b128 v[58:61], v212 offset:47104
	v_add_f32_dpp v116, v116, v116 row_ror:8 row_mask:0xf bank_mask:0xf bound_ctrl:1
	ds_read_b128 v[66:69], v212 offset:6144
	v_pk_fma_f32 v[46:47], v[116:117], v[78:79], v[124:125] op_sel_hi:[0,1,1]
	v_pk_fma_f32 v[48:49], v[116:117], v[80:81], v[126:127] op_sel_hi:[0,1,1]
	ds_read2st64_b32 v[110:111], v213 offset0:120 offset1:121
	s_waitcnt lgkmcnt(6)
	v_pk_mul_f32 v[114:115], v[46:47], v[90:91]
	v_pk_mul_f32 v[118:119], v[46:47], v[86:87]
	v_pk_fma_f32 v[114:115], v[48:49], v[92:93], v[114:115]
	v_pk_fma_f32 v[118:119], v[48:49], v[88:89], v[118:119]
	v_add_f32_e32 v116, v114, v115
	v_add_f32_e32 v135, v118, v119
	v_pk_mul_f32 v[120:121], v[102:103], v[112:113] op_sel:[0,1] op_sel_hi:[1,1]
	v_pk_mul_f32 v[122:123], v[104:105], v[112:113] op_sel:[0,1] op_sel_hi:[1,1]
	v_add_f32_dpp v116, v116, v116 quad_perm:[1,0,3,2] row_mask:0xf bank_mask:0xf bound_ctrl:1
	v_add_f32_dpp v189, v189, v189 row_ror:4 row_mask:0xf bank_mask:0xf bound_ctrl:1
	v_pk_fma_f32 v[124:125], v[46:47], v[94:95], v[120:121]
	v_pk_fma_f32 v[126:127], v[48:49], v[96:97], v[122:123]
	v_add_f32_dpp v116, v116, v116 quad_perm:[2,3,0,1] row_mask:0xf bank_mask:0xf bound_ctrl:1
	v_add_f32_dpp v189, v189, v189 row_ror:8 row_mask:0xf bank_mask:0xf bound_ctrl:1
	ds_read_b128 v[70:73], v212 offset:39168
	ds_read_b128 v[82:85], v212 offset:22784
	v_add_f32_dpp v116, v116, v116 row_ror:4 row_mask:0xf bank_mask:0xf bound_ctrl:1
	ds_write_b32 v211, v189 offset:1024
	ds_read_b128 v[74:77], v212 offset:14592
	ds_read_b128 v[78:81], v212 offset:47360
	v_add_f32_dpp v116, v116, v116 row_ror:8 row_mask:0xf bank_mask:0xf bound_ctrl:1
	ds_read_b128 v[86:89], v212 offset:6400
	v_pk_fma_f32 v[46:47], v[116:117], v[98:99], v[124:125] op_sel_hi:[0,1,1]
	v_pk_fma_f32 v[48:49], v[116:117], v[100:101], v[126:127] op_sel_hi:[0,1,1]
	s_waitcnt lgkmcnt(6)
; __device__ __forceinline__ void rwkv_prompt_unit(const Params& p, int l, int b, int h, int ibase, float* sf) {
;     ...
;             for (int g = 0; g < 16; ++g) {
;                 f32x4 Rn[2], Wn[2], Kn[2], An[2], Bn[2]; float Vn[2];
;                 if (g + 1 < 16) RW_LOAD(Rn, Wn, Kn, An, Bn, Vn, g + 1);
;                 __builtin_amdgcn_sched_barrier(0);
; #pragma unroll
;                 for (int u = 0; u < 2; ++u) {
;                     const f32x2v a01 = {A[u].x, A[u].y}, a23 = {A[u].z, A[u].w}, w01 = {W[u].x, W[u].y}, w23 = {W[u].z, W[u].w}, b01 = {B[u].x, B[u].y}, b23 = {B[u].z, B[u].w};
;                     const f32x2v k01 = {K[u].x, K[u].y}, k23 = {K[u].z, K[u].w}, r01 = {R[u].x, R[u].y}, r23 = {R[u].z, R[u].w};
;                     f32x2v pa = S01 * a01; pa = __builtin_elementwise_fma(S23, a23, pa);
;                     float ra = pa.x + pa.y, rb = pyprev;
;                     ra += dppf<0xB1, 0xF>(ra); rb += dppf<0xB1, 0xF>(rb);
;                     ra += dppf<0x4E, 0xF>(ra); rb += dppf<0x4E, 0xF>(rb);
;                     ra += dppf<0x124, 0xF>(ra); rb += dppf<0x124, 0xF>(rb);
;                     ra += dppf<0x128, 0xF>(ra); rb += dppf<0x128, 0xF>(rb);
;                     if ((g * 2 + u) > 0 && (lane & 15) == 0) sY[(g * 2 + u - 1) * 16 + rl] = rb;
;                     const f32x2v sa2 = {ra, ra}, v2 = {V[u], V[u]};
;                     S01 = __builtin_elementwise_fma(S01, w01, __builtin_elementwise_fma(sa2, b01, v2 * k01));
;                     S23 = __builtin_elementwise_fma(S23, w23, __builtin_elementwise_fma(sa2, b23, v2 * k23));
;                     f32x2v py = S01 * r01; py = __builtin_elementwise_fma(S23, r23, py);
;                     pyprev = py.x + py.y;
;                 }
;                 __builtin_amdgcn_sched_barrier(0);
;                 if (g + 1 < 16) {
; #pragma unroll
;                     for (int u = 0; u < 2; ++u) { R[u] = Rn[u]; W[u] = Wn[u]; K[u] = Kn[u]; A[u] = An[u]; B[u] = Bn[u]; V[u] = Vn[u]; }
;                 }
;             }
	v_pk_mul_f32 v[114:115], v[46:47], v[50:51]
	v_pk_mul_f32 v[118:119], v[46:47], v[106:107]
	v_pk_fma_f32 v[114:115], v[48:49], v[52:53], v[114:115]
	v_pk_fma_f32 v[118:119], v[48:49], v[108:109], v[118:119]
	v_add_f32_e32 v116, v114, v115
	v_add_f32_e32 v136, v118, v119
	v_pk_mul_f32 v[120:121], v[62:63], v[110:111] op_sel_hi:[1,0]
	v_pk_mul_f32 v[122:123], v[64:65], v[110:111] op_sel_hi:[1,0]
	v_add_f32_dpp v116, v116, v116 quad_perm:[1,0,3,2] row_mask:0xf bank_mask:0xf bound_ctrl:1
	v_cndmask_b32_e64 v137, v133, v134, s[8:9]
	v_pk_fma_f32 v[124:125], v[46:47], v[54:55], v[120:121]
	v_pk_fma_f32 v[126:127], v[48:49], v[56:57], v[122:123]
	v_add_f32_dpp v116, v116, v116 quad_perm:[2,3,0,1] row_mask:0xf bank_mask:0xf bound_ctrl:1
	v_cndmask_b32_e64 v186, v134, v133, s[8:9]
	ds_read_b128 v[90:93], v212 offset:39424
	ds_read_b128 v[102:105], v212 offset:23040
	v_add_f32_dpp v116, v116, v116 row_ror:4 row_mask:0xf bank_mask:0xf bound_ctrl:1
	v_add_f32_dpp v187, v186, v137 quad_perm:[1,0,3,2] row_mask:0xf bank_mask:0xf bound_ctrl:1
	ds_read_b128 v[94:97], v212 offset:14848
	ds_read_b128 v[98:101], v212 offset:47616
	v_add_f32_dpp v116, v116, v116 row_ror:8 row_mask:0xf bank_mask:0xf bound_ctrl:1
	ds_read_b128 v[106:109], v212 offset:6656
	v_pk_fma_f32 v[46:47], v[116:117], v[58:59], v[124:125] op_sel_hi:[0,1,1]
	v_pk_fma_f32 v[48:49], v[116:117], v[60:61], v[126:127] op_sel_hi:[0,1,1]
	ds_read2st64_b32 v[112:113], v213 offset0:122 offset1:123
	s_waitcnt lgkmcnt(6)
	v_pk_mul_f32 v[114:115], v[46:47], v[70:71]
	v_pk_mul_f32 v[118:119], v[46:47], v[66:67]
	v_pk_fma_f32 v[114:115], v[48:49], v[72:73], v[114:115]
	v_pk_fma_f32 v[118:119], v[48:49], v[68:69], v[118:119]
	v_add_f32_e32 v116, v114, v115
	v_add_f32_e32 v129, v118, v119
	v_pk_mul_f32 v[120:121], v[82:83], v[110:111] op_sel:[0,1] op_sel_hi:[1,1]
	v_pk_mul_f32 v[122:123], v[84:85], v[110:111] op_sel:[0,1] op_sel_hi:[1,1]
	v_add_f32_dpp v116, v116, v116 quad_perm:[1,0,3,2] row_mask:0xf bank_mask:0xf bound_ctrl:1
	v_cndmask_b32_e64 v137, v135, v136, s[8:9]
	v_pk_fma_f32 v[124:125], v[46:47], v[74:75], v[120:121]
	v_pk_fma_f32 v[126:127], v[48:49], v[76:77], v[122:123]
	v_add_f32_dpp v116, v116, v116 quad_perm:[2,3,0,1] row_mask:0xf bank_mask:0xf bound_ctrl:1
	v_cndmask_b32_e64 v186, v136, v135, s[8:9]
	ds_read_b128 v[50:53], v212 offset:39680
	ds_read_b128 v[62:65], v212 offset:23296
	v_add_f32_dpp v116, v116, v116 row_ror:4 row_mask:0xf bank_mask:0xf bound_ctrl:1
	v_add_f32_dpp v188, v186, v137 quad_perm:[1,0,3,2] row_mask:0xf bank_mask:0xf bound_ctrl:1
	ds_read_b128 v[54:57], v212 offset:15104
	ds_read_b128 v[58:61], v212 offset:47872
	v_add_f32_dpp v116, v116, v116 row_ror:8 row_mask:0xf bank_mask:0xf bound_ctrl:1
	ds_read_b128 v[66:69], v212 offset:6912
	v_pk_fma_f32 v[46:47], v[116:117], v[78:79], v[124:125] op_sel_hi:[0,1,1]
	v_pk_fma_f32 v[48:49], v[116:117], v[80:81], v[126:127] op_sel_hi:[0,1,1]
	s_waitcnt lgkmcnt(5)
	v_pk_mul_f32 v[114:115], v[46:47], v[90:91]
	v_pk_mul_f32 v[118:119], v[46:47], v[86:87]
	v_pk_fma_f32 v[114:115], v[48:49], v[92:93], v[114:115]
	v_pk_fma_f32 v[118:119], v[48:49], v[88:89], v[118:119]
	v_add_f32_e32 v116, v114, v115
	v_add_f32_e32 v130, v118, v119
	v_pk_mul_f32 v[120:121], v[102:103], v[112:113] op_sel_hi:[1,0]
	v_pk_mul_f32 v[122:123], v[104:105], v[112:113] op_sel_hi:[1,0]
	v_add_f32_dpp v116, v116, v116 quad_perm:[1,0,3,2] row_mask:0xf bank_mask:0xf bound_ctrl:1
	v_cndmask_b32_e32 v137, v187, v188, vcc
	v_pk_fma_f32 v[124:125], v[46:47], v[94:95], v[120:121]
	v_pk_fma_f32 v[126:127], v[48:49], v[96:97], v[122:123]
	v_add_f32_dpp v116, v116, v116 quad_perm:[2,3,0,1] row_mask:0xf bank_mask:0xf bound_ctrl:1
	v_cndmask_b32_e32 v186, v188, v187, vcc
	ds_read_b128 v[70:73], v212 offset:39936
	ds_read_b128 v[82:85], v212 offset:23552
	v_add_f32_dpp v116, v116, v116 row_ror:4 row_mask:0xf bank_mask:0xf bound_ctrl:1
	v_add_f32_dpp v189, v186, v137 quad_perm:[2,3,0,1] row_mask:0xf bank_mask:0xf bound_ctrl:1
	ds_read_b128 v[74:77], v212 offset:15360
	ds_read_b128 v[78:81], v212 offset:48128
	v_add_f32_dpp v116, v116, v116 row_ror:8 row_mask:0xf bank_mask:0xf bound_ctrl:1
	ds_read_b128 v[86:89], v212 offset:7168
	v_pk_fma_f32 v[46:47], v[116:117], v[98:99], v[124:125] op_sel_hi:[0,1,1]
	v_pk_fma_f32 v[48:49], v[116:117], v[100:101], v[126:127] op_sel_hi:[0,1,1]
	ds_read2st64_b32 v[110:111], v213 offset0:124 offset1:125
	s_waitcnt lgkmcnt(6)
	v_pk_mul_f32 v[114:115], v[46:47], v[50:51]
	v_pk_mul_f32 v[118:119], v[46:47], v[106:107]
	v_pk_fma_f32 v[114:115], v[48:49], v[52:53], v[114:115]
	v_pk_fma_f32 v[118:119], v[48:49], v[108:109], v[118:119]
	v_add_f32_e32 v116, v114, v115
	v_add_f32_e32 v131, v118, v119
	v_pk_mul_f32 v[120:121], v[62:63], v[112:113] op_sel:[0,1] op_sel_hi:[1,1]
	v_pk_mul_f32 v[122:123], v[64:65], v[112:113] op_sel:[0,1] op_sel_hi:[1,1]
	v_add_f32_dpp v116, v116, v116 quad_perm:[1,0,3,2] row_mask:0xf bank_mask:0xf bound_ctrl:1
	v_add_f32_dpp v189, v189, v189 row_ror:4 row_mask:0xf bank_mask:0xf bound_ctrl:1
	v_pk_fma_f32 v[124:125], v[46:47], v[54:55], v[120:121]
	v_pk_fma_f32 v[126:127], v[48:49], v[56:57], v[122:123]
	v_add_f32_dpp v116, v116, v116 quad_perm:[2,3,0,1] row_mask:0xf bank_mask:0xf bound_ctrl:1
	v_add_f32_dpp v189, v189, v189 row_ror:8 row_mask:0xf bank_mask:0xf bound_ctrl:1
	ds_read_b128 v[90:93], v212 offset:40192
	ds_read_b128 v[102:105], v212 offset:23808
	v_add_f32_dpp v116, v116, v116 row_ror:4 row_mask:0xf bank_mask:0xf bound_ctrl:1
	ds_write_b32 v211, v189 offset:1280
	ds_read_b128 v[94:97], v212 offset:15616
	ds_read_b128 v[98:101], v212 offset:48384
	v_add_f32_dpp v116, v116, v116 row_ror:8 row_mask:0xf bank_mask:0xf bound_ctrl:1
	ds_read_b128 v[106:109], v212 offset:7424
	v_pk_fma_f32 v[46:47], v[116:117], v[58:59], v[124:125] op_sel_hi:[0,1,1]
	v_pk_fma_f32 v[48:49], v[116:117], v[60:61], v[126:127] op_sel_hi:[0,1,1]
	s_waitcnt lgkmcnt(6)
; __device__ __forceinline__ float row_sum16(float x) { x += __shfl_xor(x, 1); x += __shfl_xor(x, 2); x += __shfl_xor(x, 4); x += __shfl_xor(x, 8); return x; }
; __device__ __forceinline__ void rwkv_prompt_unit(const Params& p, int l, int b, int h, int ibase, float* sf) {
;     ...
;             for (int g = 0; g < 16; ++g) {
;                 f32x4 Rn[2], Wn[2], Kn[2], An[2], Bn[2]; float Vn[2];
;                 if (g + 1 < 16) RW_LOAD(Rn, Wn, Kn, An, Bn, Vn, g + 1);
;                 __builtin_amdgcn_sched_barrier(0);
; #pragma unroll
;                 for (int u = 0; u < 2; ++u) {
;                     const f32x2v a01 = {A[u].x, A[u].y}, a23 = {A[u].z, A[u].w}, w01 = {W[u].x, W[u].y}, w23 = {W[u].z, W[u].w}, b01 = {B[u].x, B[u].y}, b23 = {B[u].z, B[u].w};
;                     const f32x2v k01 = {K[u].x, K[u].y}, k23 = {K[u].z, K[u].w}, r01 = {R[u].x, R[u].y}, r23 = {R[u].z, R[u].w};
;                     f32x2v pa = S01 * a01; pa = __builtin_elementwise_fma(S23, a23, pa);
;                     float ra = pa.x + pa.y, rb = pyprev;
;                     ra += dppf<0xB1, 0xF>(ra); rb += dppf<0xB1, 0xF>(rb);
;                     ra += dppf<0x4E, 0xF>(ra); rb += dppf<0x4E, 0xF>(rb);
;                     ra += dppf<0x124, 0xF>(ra); rb += dppf<0x124, 0xF>(rb);
;                     ra += dppf<0x128, 0xF>(ra); rb += dppf<0x128, 0xF>(rb);
;                     if ((g * 2 + u) > 0 && (lane & 15) == 0) sY[(g * 2 + u - 1) * 16 + rl] = rb;
;                     const f32x2v sa2 = {ra, ra}, v2 = {V[u], V[u]};
;                     S01 = __builtin_elementwise_fma(S01, w01, __builtin_elementwise_fma(sa2, b01, v2 * k01));
;                     S23 = __builtin_elementwise_fma(S23, w23, __builtin_elementwise_fma(sa2, b23, v2 * k23));
;                     f32x2v py = S01 * r01; py = __builtin_elementwise_fma(S23, r23, py);
;                     pyprev = py.x + py.y;
;                 }
;                 __builtin_amdgcn_sched_barrier(0);
;                 if (g + 1 < 16) {
; #pragma unroll
;                     for (int u = 0; u < 2; ++u) { R[u] = Rn[u]; W[u] = Wn[u]; K[u] = Kn[u]; A[u] = An[u]; B[u] = Bn[u]; V[u] = Vn[u]; }
;                 }
;             }
;     ...
;             { const float yl = row_sum16(pyprev); if ((lane & 15) == 0) sY[31 * 16 + rl] = yl; }
	v_pk_mul_f32 v[114:115], v[46:47], v[70:71]
	v_pk_mul_f32 v[118:119], v[46:47], v[66:67]
	v_pk_fma_f32 v[114:115], v[48:49], v[72:73], v[114:115]
	v_pk_fma_f32 v[118:119], v[48:49], v[68:69], v[118:119]
	v_add_f32_e32 v116, v114, v115
	v_add_f32_e32 v132, v118, v119
	v_pk_mul_f32 v[120:121], v[82:83], v[110:111] op_sel_hi:[1,0]
	v_pk_mul_f32 v[122:123], v[84:85], v[110:111] op_sel_hi:[1,0]
	v_add_f32_dpp v116, v116, v116 quad_perm:[1,0,3,2] row_mask:0xf bank_mask:0xf bound_ctrl:1
	v_cndmask_b32_e64 v137, v129, v130, s[8:9]
	v_pk_fma_f32 v[124:125], v[46:47], v[74:75], v[120:121]
	v_pk_fma_f32 v[126:127], v[48:49], v[76:77], v[122:123]
	v_add_f32_dpp v116, v116, v116 quad_perm:[2,3,0,1] row_mask:0xf bank_mask:0xf bound_ctrl:1
	v_cndmask_b32_e64 v186, v130, v129, s[8:9]
	ds_read_b128 v[50:53], v212 offset:40448
	ds_read_b128 v[62:65], v212 offset:24064
	v_add_f32_dpp v116, v116, v116 row_ror:4 row_mask:0xf bank_mask:0xf bound_ctrl:1
	v_add_f32_dpp v187, v186, v137 quad_perm:[1,0,3,2] row_mask:0xf bank_mask:0xf bound_ctrl:1
	ds_read_b128 v[54:57], v212 offset:15872
	ds_read_b128 v[58:61], v212 offset:48640
	v_add_f32_dpp v116, v116, v116 row_ror:8 row_mask:0xf bank_mask:0xf bound_ctrl:1
	ds_read_b128 v[66:69], v212 offset:7680
	v_pk_fma_f32 v[46:47], v[116:117], v[78:79], v[124:125] op_sel_hi:[0,1,1]
	v_pk_fma_f32 v[48:49], v[116:117], v[80:81], v[126:127] op_sel_hi:[0,1,1]
	ds_read2st64_b32 v[112:113], v213 offset0:126 offset1:127
	s_waitcnt lgkmcnt(6)
	v_pk_mul_f32 v[114:115], v[46:47], v[90:91]
	v_pk_mul_f32 v[118:119], v[46:47], v[86:87]
	v_pk_fma_f32 v[114:115], v[48:49], v[92:93], v[114:115]
	v_pk_fma_f32 v[118:119], v[48:49], v[88:89], v[118:119]
	v_add_f32_e32 v116, v114, v115
	v_add_f32_e32 v133, v118, v119
	v_pk_mul_f32 v[120:121], v[102:103], v[110:111] op_sel:[0,1] op_sel_hi:[1,1]
	v_pk_mul_f32 v[122:123], v[104:105], v[110:111] op_sel:[0,1] op_sel_hi:[1,1]
	v_add_f32_dpp v116, v116, v116 quad_perm:[1,0,3,2] row_mask:0xf bank_mask:0xf bound_ctrl:1
	v_cndmask_b32_e64 v137, v131, v132, s[8:9]
	v_pk_fma_f32 v[124:125], v[46:47], v[94:95], v[120:121]
	v_pk_fma_f32 v[126:127], v[48:49], v[96:97], v[122:123]
	v_add_f32_dpp v116, v116, v116 quad_perm:[2,3,0,1] row_mask:0xf bank_mask:0xf bound_ctrl:1
	v_cndmask_b32_e64 v186, v132, v131, s[8:9]
	ds_read_b128 v[70:73], v212 offset:40704
	ds_read_b128 v[82:85], v212 offset:24320
	v_add_f32_dpp v116, v116, v116 row_ror:4 row_mask:0xf bank_mask:0xf bound_ctrl:1
	v_add_f32_dpp v188, v186, v137 quad_perm:[1,0,3,2] row_mask:0xf bank_mask:0xf bound_ctrl:1
	ds_read_b128 v[74:77], v212 offset:16128
	ds_read_b128 v[78:81], v212 offset:48896
	v_add_f32_dpp v116, v116, v116 row_ror:8 row_mask:0xf bank_mask:0xf bound_ctrl:1
	ds_read_b128 v[86:89], v212 offset:7936
	v_pk_fma_f32 v[46:47], v[116:117], v[98:99], v[124:125] op_sel_hi:[0,1,1]
	v_pk_fma_f32 v[48:49], v[116:117], v[100:101], v[126:127] op_sel_hi:[0,1,1]
	s_waitcnt lgkmcnt(5)
	v_pk_mul_f32 v[114:115], v[46:47], v[50:51]
	v_pk_mul_f32 v[118:119], v[46:47], v[106:107]
	v_pk_fma_f32 v[114:115], v[48:49], v[52:53], v[114:115]
	v_pk_fma_f32 v[118:119], v[48:49], v[108:109], v[118:119]
	v_add_f32_e32 v116, v114, v115
	v_add_f32_e32 v134, v118, v119
	v_pk_mul_f32 v[120:121], v[62:63], v[112:113] op_sel_hi:[1,0]
	v_pk_mul_f32 v[122:123], v[64:65], v[112:113] op_sel_hi:[1,0]
	v_add_f32_dpp v116, v116, v116 quad_perm:[1,0,3,2] row_mask:0xf bank_mask:0xf bound_ctrl:1
	v_cndmask_b32_e32 v137, v187, v188, vcc
	v_pk_fma_f32 v[124:125], v[46:47], v[54:55], v[120:121]
	v_pk_fma_f32 v[126:127], v[48:49], v[56:57], v[122:123]
	v_add_f32_dpp v116, v116, v116 quad_perm:[2,3,0,1] row_mask:0xf bank_mask:0xf bound_ctrl:1
	v_cndmask_b32_e32 v186, v188, v187, vcc
	s_nop 0
	v_add_f32_dpp v116, v116, v116 row_ror:4 row_mask:0xf bank_mask:0xf bound_ctrl:1
	v_add_f32_dpp v189, v186, v137 quad_perm:[2,3,0,1] row_mask:0xf bank_mask:0xf bound_ctrl:1
	s_nop 0
	v_add_f32_dpp v116, v116, v116 row_ror:8 row_mask:0xf bank_mask:0xf bound_ctrl:1
	v_pk_fma_f32 v[46:47], v[116:117], v[58:59], v[124:125] op_sel_hi:[0,1,1]
	v_pk_fma_f32 v[48:49], v[116:117], v[60:61], v[126:127] op_sel_hi:[0,1,1]
	s_waitcnt lgkmcnt(0)
	v_pk_mul_f32 v[114:115], v[46:47], v[70:71]
	v_pk_mul_f32 v[118:119], v[46:47], v[66:67]
	v_pk_fma_f32 v[114:115], v[48:49], v[72:73], v[114:115]
	v_pk_fma_f32 v[118:119], v[48:49], v[68:69], v[118:119]
	v_add_f32_e32 v116, v114, v115
	v_add_f32_e32 v135, v118, v119
	v_pk_mul_f32 v[120:121], v[82:83], v[112:113] op_sel:[0,1] op_sel_hi:[1,1]
	v_pk_mul_f32 v[122:123], v[84:85], v[112:113] op_sel:[0,1] op_sel_hi:[1,1]
	v_add_f32_dpp v116, v116, v116 quad_perm:[1,0,3,2] row_mask:0xf bank_mask:0xf bound_ctrl:1
	v_add_f32_dpp v189, v189, v189 row_ror:4 row_mask:0xf bank_mask:0xf bound_ctrl:1
	v_pk_fma_f32 v[124:125], v[46:47], v[74:75], v[120:121]
	v_pk_fma_f32 v[126:127], v[48:49], v[76:77], v[122:123]
	v_add_f32_dpp v116, v116, v116 quad_perm:[2,3,0,1] row_mask:0xf bank_mask:0xf bound_ctrl:1
	v_add_f32_dpp v189, v189, v189 row_ror:8 row_mask:0xf bank_mask:0xf bound_ctrl:1
	s_nop 0
	v_add_f32_dpp v116, v116, v116 row_ror:4 row_mask:0xf bank_mask:0xf bound_ctrl:1
	ds_write_b32 v211, v189 offset:1536
	s_nop 0
	v_add_f32_dpp v116, v116, v116 row_ror:8 row_mask:0xf bank_mask:0xf bound_ctrl:1
	v_pk_fma_f32 v[46:47], v[116:117], v[78:79], v[124:125] op_sel_hi:[0,1,1]
	v_pk_fma_f32 v[48:49], v[116:117], v[80:81], v[126:127] op_sel_hi:[0,1,1]
	v_pk_mul_f32 v[118:119], v[46:47], v[86:87]
	s_nop 0
	v_pk_fma_f32 v[118:119], v[48:49], v[88:89], v[118:119]
	s_nop 0
	v_add_f32_e32 v136, v118, v119
	v_cndmask_b32_e64 v137, v133, v134, s[8:9]
	v_cndmask_b32_e64 v186, v134, v133, s[8:9]
	s_nop 1
	v_add_f32_dpp v187, v186, v137 quad_perm:[1,0,3,2] row_mask:0xf bank_mask:0xf bound_ctrl:1
	v_cndmask_b32_e64 v137, v135, v136, s[8:9]
	v_cndmask_b32_e64 v186, v136, v135, s[8:9]
	s_nop 1
	v_add_f32_dpp v188, v186, v137 quad_perm:[1,0,3,2] row_mask:0xf bank_mask:0xf bound_ctrl:1
	v_cndmask_b32_e32 v137, v187, v188, vcc
	v_cndmask_b32_e32 v186, v188, v187, vcc
	s_nop 1
	v_add_f32_dpp v189, v186, v137 quad_perm:[2,3,0,1] row_mask:0xf bank_mask:0xf bound_ctrl:1
	s_nop 1
	v_add_f32_dpp v189, v189, v189 row_ror:4 row_mask:0xf bank_mask:0xf bound_ctrl:1
	s_nop 1
	v_add_f32_dpp v189, v189, v189 row_ror:8 row_mask:0xf bank_mask:0xf bound_ctrl:1
	ds_write_b32 v211, v189 offset:1792
	s_setprio 0
	s_branch .LBB0_955
